# memory attention row-max without self-max canonicalisations; gMLP LayerNorm rstd via v_rsq_f32
# speedup vs baseline: 1.0247x; 1.0069x over previous
.LBB0_1187:
	s_waitcnt lgkmcnt(1)
	v_add_f32_e32 v75, v104, v106
	v_mul_f32_e32 v73, 0x3b000000, v75
	s_waitcnt lgkmcnt(0)
	v_add_f32_e32 v72, v105, v107
	v_mul_f32_e32 v73, v73, v73
	v_fma_f32 v72, v72, s73, -v73
	v_max_f32_e32 v72, 0, v72
	v_add_f32_e32 v72, 0x358637bd, v72
	v_fmac_f32_e32 v103, 0xbb000000, v75
	v_rsq_f32_e32 v73, v72
	v_fmac_f32_e32 v102, 0xbb000000, v75
	v_fmac_f32_e32 v101, 0xbb000000, v75
	v_fmac_f32_e32 v100, 0xbb000000, v75
	v_fmac_f32_e32 v99, 0xbb000000, v75
	v_fmac_f32_e32 v98, 0xbb000000, v75
	v_or_b32_e32 v70, s31, v66
	v_fmac_f32_e32 v96, 0xbb000000, v75
	v_lshl_add_u32 v71, v89, 4, 0
	s_movk_i32 s8, 0x120
	v_fmac_f32_e32 v97, 0xbb000000, v75
	v_mul_lo_u32 v70, v70, s8
	s_nop 0
	v_mov_b32_e32 v76, v73
	v_mul_f32_e32 v72, v76, v103
	v_mul_f32_e32 v73, v76, v102
	s_waitcnt vmcnt(21)
	v_mov_b64_e32 v[16:17], v[118:119]
	v_mov_b64_e32 v[18:19], v[120:121]
	v_mov_b64_e32 v[0:1], v[124:125]
	v_mov_b64_e32 v[2:3], v[126:127]
	v_mov_b64_e32 v[8:9], v[128:129]
	v_mov_b64_e32 v[10:11], v[130:131]
	v_mov_b64_e32 v[4:5], v[132:133]
	v_mov_b64_e32 v[6:7], v[134:135]
	v_mov_b64_e32 v[12:13], v[136:137]
	v_mov_b64_e32 v[14:15], v[138:139]
	v_fma_f32 v72, v8, v72, v12
	v_fma_f32 v73, v9, v73, v13
	v_cvt_pk_bf16_f32 v72, v72, v73
	v_mul_f32_e32 v73, v76, v101
	v_mul_f32_e32 v74, v76, v100
	v_fma_f32 v73, v10, v73, v14
	v_fma_f32 v74, v11, v74, v15
	v_cvt_pk_bf16_f32 v73, v73, v74
	v_mul_f32_e32 v74, v76, v99
	v_mul_f32_e32 v77, v76, v98
	v_fma_f32 v74, v0, v74, v4
	v_fma_f32 v77, v1, v77, v5
	v_mul_f32_e32 v75, v76, v96
	v_cvt_pk_bf16_f32 v74, v74, v77
	v_mul_f32_e32 v77, v76, v97
	v_fma_f32 v75, v3, v75, v7
	v_add_u32_e32 v70, v71, v70
	v_fma_f32 v77, v2, v77, v6
	v_cvt_pk_bf16_f32 v75, v77, v75
	ds_write_b128 v70, v[72:75]
	v_lshlrev_b32_e32 v71, 16, v62
	v_and_b32_e32 v62, 0xffff0000, v62
	v_lshlrev_b32_e32 v72, 16, v63
	v_and_b32_e32 v63, 0xffff0000, v63
	v_lshlrev_b32_e32 v73, 16, v64
	v_and_b32_e32 v64, 0xffff0000, v64
	v_lshlrev_b32_e32 v74, 16, v65
	v_and_b32_e32 v65, 0xffff0000, v65
	v_add_f32_e32 v75, v71, v62
	v_add_f32_e32 v76, v72, v63
	v_add_f32_e32 v75, v75, v76
	v_add_f32_e32 v76, v73, v64
	v_add_f32_e32 v77, v74, v65
	v_add_f32_e32 v76, v76, v77
	v_add_f32_e32 v75, v75, v76
	v_add_f32_e32 v79, 0, v75
	v_mul_f32_e32 v75, v62, v62
	v_mul_f32_e32 v76, v63, v63
	v_fmac_f32_e32 v75, v71, v71
	v_fmac_f32_e32 v76, v72, v72
	v_add_f32_e32 v75, v75, v76
	v_mul_f32_e32 v76, v64, v64
	v_mul_f32_e32 v77, v65, v65
	v_fmac_f32_e32 v76, v73, v73
	v_fmac_f32_e32 v77, v74, v74
	v_add_f32_e32 v76, v76, v77
	v_add_f32_e32 v80, v75, v76
	v_lshlrev_b32_e32 v75, 16, v58
	v_and_b32_e32 v58, 0xffff0000, v58
	v_lshlrev_b32_e32 v76, 16, v59
	v_and_b32_e32 v59, 0xffff0000, v59
	v_lshlrev_b32_e32 v77, 16, v60
	v_and_b32_e32 v60, 0xffff0000, v60
	v_lshlrev_b32_e32 v78, 16, v61
	v_and_b32_e32 v61, 0xffff0000, v61
	v_add_f32_e32 v81, v75, v58
	v_add_f32_e32 v82, v76, v59
	v_add_f32_e32 v81, v81, v82
	v_add_f32_e32 v82, v77, v60
	v_add_f32_e32 v83, v78, v61
	v_add_f32_e32 v82, v82, v83
	v_add_f32_e32 v81, v81, v82
	v_add_f32_e32 v79, v79, v81
	v_mul_f32_e32 v81, v58, v58
	v_mul_f32_e32 v82, v59, v59
	v_fmac_f32_e32 v81, v75, v75
	v_fmac_f32_e32 v82, v76, v76
	v_add_f32_e32 v81, v81, v82
	v_mul_f32_e32 v82, v60, v60
	v_mul_f32_e32 v83, v61, v61
	v_fmac_f32_e32 v82, v77, v77
	v_fmac_f32_e32 v83, v78, v78
	v_add_f32_e32 v82, v82, v83
	v_add_f32_e32 v81, v81, v82
	v_add_f32_e32 v90, v80, v81
	v_lshlrev_b32_e32 v80, 16, v54
	v_and_b32_e32 v81, 0xffff0000, v54
	v_lshlrev_b32_e32 v82, 16, v55
	v_and_b32_e32 v83, 0xffff0000, v55
	v_lshlrev_b32_e32 v84, 16, v56
	v_and_b32_e32 v85, 0xffff0000, v56
	v_lshlrev_b32_e32 v86, 16, v57
	v_and_b32_e32 v87, 0xffff0000, v57
	v_add_f32_e32 v54, v80, v81
	v_add_f32_e32 v55, v82, v83
	v_add_f32_e32 v54, v54, v55
	v_add_f32_e32 v55, v84, v85
	v_add_f32_e32 v56, v86, v87
	v_add_f32_e32 v55, v55, v56
	v_add_f32_e32 v54, v54, v55
	v_add_f32_e32 v91, v79, v54
	v_mul_f32_e32 v54, v81, v81
	v_mul_f32_e32 v55, v83, v83
	v_fmac_f32_e32 v54, v80, v80
	v_fmac_f32_e32 v55, v82, v82
	v_add_f32_e32 v54, v54, v55
	v_mul_f32_e32 v55, v85, v85
	v_mul_f32_e32 v56, v87, v87
	v_fmac_f32_e32 v55, v84, v84
	v_fmac_f32_e32 v56, v86, v86
	v_add_f32_e32 v55, v55, v56
	v_add_f32_e32 v54, v54, v55
	v_lshlrev_b32_e32 v79, 16, v50
	v_and_b32_e32 v57, 0xffff0000, v50
	v_lshlrev_b32_e32 v56, 16, v51
	v_and_b32_e32 v55, 0xffff0000, v51
	v_add_f32_e32 v90, v90, v54
	v_lshlrev_b32_e32 v54, 16, v52
	v_and_b32_e32 v52, 0xffff0000, v52
	v_lshlrev_b32_e32 v51, 16, v53
	v_and_b32_e32 v50, 0xffff0000, v53
	v_add_f32_e32 v53, v79, v57
	v_add_f32_e32 v92, v56, v55
	v_add_f32_e32 v53, v53, v92
	v_add_f32_e32 v92, v54, v52
	v_add_f32_e32 v93, v51, v50
	v_add_f32_e32 v92, v92, v93
	v_add_f32_e32 v53, v53, v92
	v_add_f32_e32 v53, v91, v53
	v_mul_f32_e32 v91, v57, v57
	v_mul_f32_e32 v92, v55, v55
	v_fmac_f32_e32 v91, v79, v79
	v_fmac_f32_e32 v92, v56, v56
	v_add_f32_e32 v91, v91, v92
	v_mul_f32_e32 v92, v52, v52
	v_mul_f32_e32 v93, v50, v50
	v_fmac_f32_e32 v92, v54, v54
	v_fmac_f32_e32 v93, v51, v51
	v_add_f32_e32 v92, v92, v93
	v_add_f32_e32 v91, v91, v92
	v_add_f32_e32 v90, v90, v91
	s_nop 1
	v_mov_b32_dpp v91, v53 quad_perm:[1,0,3,2] row_mask:0xf bank_mask:0xf
	s_cmp_lt_i32 s65, 2
	s_mov_b64 s[10:11], -1
	s_waitcnt lgkmcnt(0)
	v_add_f32_e32 v53, v53, v91
	s_nop 1
	v_mov_b32_dpp v91, v90 quad_perm:[1,0,3,2] row_mask:0xf bank_mask:0xf
	s_waitcnt lgkmcnt(0)
	v_add_f32_e32 v90, v90, v91
	s_nop 1
	v_mov_b32_dpp v91, v53 quad_perm:[2,3,0,1] row_mask:0xf bank_mask:0xf
	s_waitcnt lgkmcnt(0)
	v_add_f32_e32 v53, v53, v91
	s_nop 1
	v_mov_b32_dpp v91, v90 quad_perm:[2,3,0,1] row_mask:0xf bank_mask:0xf
	s_waitcnt lgkmcnt(0)
	v_add_f32_e32 v90, v90, v91
	s_nop 1
	v_mov_b32_dpp v91, v53 row_half_mirror row_mask:0xf bank_mask:0xf
	s_waitcnt lgkmcnt(0)
	v_add_f32_e32 v53, v53, v91
	s_nop 1
	v_mov_b32_dpp v91, v90 row_half_mirror row_mask:0xf bank_mask:0xf
	s_waitcnt lgkmcnt(0)
	v_add_f32_e32 v90, v90, v91
	s_nop 1
	v_mov_b32_dpp v91, v53 row_mirror row_mask:0xf bank_mask:0xf
	s_nop 1
	v_mov_b32_dpp v92, v90 row_mirror row_mask:0xf bank_mask:0xf
	s_cbranch_scc1 .LBB0_1191
	s_cmp_lt_i32 s65, 3
	s_cbranch_scc0 .LBB0_1190
	v_mov_b32_e32 v79, v80
	v_mov_b32_e32 v57, v81
	v_mov_b32_e32 v56, v82
	v_mov_b32_e32 v55, v83
	v_mov_b32_e32 v54, v84
	v_mov_b32_e32 v52, v85
	v_mov_b32_e32 v51, v86
	v_mov_b32_e32 v50, v87

.LBB0_1197:
	s_waitcnt lgkmcnt(1)
	v_add_f32_e32 v53, v53, v91
	v_mul_f32_e32 v59, 0x3b000000, v53
	s_waitcnt lgkmcnt(0)
	v_add_f32_e32 v58, v90, v92
	v_mul_f32_e32 v59, v59, v59
	v_fma_f32 v58, v58, s73, -v59
	v_max_f32_e32 v58, 0, v58
	v_add_f32_e32 v58, 0x358637bd, v58
	v_fmac_f32_e32 v51, 0xbb000000, v53
	v_rsq_f32_e32 v59, v58
	v_fmac_f32_e32 v50, 0xbb000000, v53
	v_fmac_f32_e32 v55, 0xbb000000, v53
	v_fmac_f32_e32 v54, 0xbb000000, v53
	v_fmac_f32_e32 v52, 0xbb000000, v53
	v_fmac_f32_e32 v79, 0xbb000000, v53
	v_fmac_f32_e32 v57, 0xbb000000, v53
	v_fmac_f32_e32 v56, 0xbb000000, v53
	v_lshlrev_b32_e32 v53, 16, v49
	v_and_b32_e32 v49, 0xffff0000, v49
	v_and_b32_e32 v64, 0xffff0000, v40
	v_lshlrev_b32_e32 v65, 16, v41
	s_nop 0
	v_mov_b32_e32 v61, v59
	v_mul_f32_e32 v51, v61, v51
	v_mul_f32_e32 v50, v61, v50
	v_mul_f32_e32 v55, v61, v55
	v_mul_f32_e32 v54, v61, v54
	v_mul_f32_e32 v52, v61, v52
	v_fma_f32 v51, v2, v51, v6
	v_fma_f32 v50, v3, v50, v7
	v_mul_f32_e32 v58, v61, v79
	v_mul_f32_e32 v57, v61, v57
	v_mul_f32_e32 v56, v61, v56
	v_fma_f32 v55, v11, v55, v15
	v_fma_f32 v54, v0, v54, v4
	v_fma_f32 v52, v1, v52, v5
	v_cvt_pk_bf16_f32 v61, v51, v50
	v_lshlrev_b32_e32 v50, 16, v46
	v_and_b32_e32 v46, 0xffff0000, v46
	v_lshlrev_b32_e32 v51, 16, v47
	v_and_b32_e32 v47, 0xffff0000, v47
	v_fma_f32 v56, v10, v56, v14
	v_cvt_pk_bf16_f32 v59, v56, v55
	v_cvt_pk_bf16_f32 v60, v54, v52
	v_lshlrev_b32_e32 v52, 16, v48
	v_and_b32_e32 v48, 0xffff0000, v48
	v_add_f32_e32 v54, v50, v46
	v_add_f32_e32 v55, v51, v47
	v_add_f32_e32 v54, v54, v55
	v_add_f32_e32 v55, v52, v48
	v_add_f32_e32 v56, v53, v49
	v_fma_f32 v58, v8, v58, v12
	v_add_f32_e32 v55, v55, v56
	v_fma_f32 v57, v9, v57, v13
	v_cvt_pk_bf16_f32 v58, v58, v57
	v_add_f32_e32 v54, v54, v55
	ds_write_b128 v70, v[58:61] offset:1152
	v_add_f32_e32 v58, 0, v54
	v_mul_f32_e32 v54, v46, v46
	v_mul_f32_e32 v55, v47, v47
	v_fmac_f32_e32 v54, v50, v50
	v_fmac_f32_e32 v55, v51, v51
	v_add_f32_e32 v54, v54, v55
	v_mul_f32_e32 v55, v48, v48
	v_mul_f32_e32 v56, v49, v49
	v_fmac_f32_e32 v55, v52, v52
	v_fmac_f32_e32 v56, v53, v53
	v_add_f32_e32 v55, v55, v56
	v_add_f32_e32 v59, v54, v55
	v_lshlrev_b32_e32 v54, 16, v42
	v_and_b32_e32 v42, 0xffff0000, v42
	v_lshlrev_b32_e32 v55, 16, v43
	v_and_b32_e32 v43, 0xffff0000, v43
	v_lshlrev_b32_e32 v56, 16, v44
	v_and_b32_e32 v44, 0xffff0000, v44
	v_lshlrev_b32_e32 v57, 16, v45
	v_and_b32_e32 v45, 0xffff0000, v45
	v_add_f32_e32 v60, v54, v42
	v_add_f32_e32 v61, v55, v43
	v_add_f32_e32 v60, v60, v61
	v_add_f32_e32 v61, v56, v44
	v_add_f32_e32 v62, v57, v45
	v_add_f32_e32 v61, v61, v62
	v_add_f32_e32 v60, v60, v61
	v_add_f32_e32 v58, v58, v60
	v_mul_f32_e32 v60, v42, v42
	v_mul_f32_e32 v61, v43, v43
	v_fmac_f32_e32 v60, v54, v54
	v_fmac_f32_e32 v61, v55, v55
	v_add_f32_e32 v60, v60, v61
	v_mul_f32_e32 v61, v44, v44
	v_mul_f32_e32 v62, v45, v45
	v_fmac_f32_e32 v61, v56, v56
	v_fmac_f32_e32 v62, v57, v57
	v_add_f32_e32 v61, v61, v62
	v_add_f32_e32 v60, v60, v61
	v_add_f32_e32 v72, v59, v60
	v_lshlrev_b32_e32 v59, 16, v38
	v_and_b32_e32 v60, 0xffff0000, v38
	v_lshlrev_b32_e32 v61, 16, v39
	v_and_b32_e32 v62, 0xffff0000, v39
	v_lshlrev_b32_e32 v63, 16, v40
	v_and_b32_e32 v71, 0xffff0000, v41
	v_add_f32_e32 v38, v59, v60
	v_add_f32_e32 v39, v61, v62
	v_add_f32_e32 v38, v38, v39
	v_add_f32_e32 v39, v63, v64
	v_add_f32_e32 v40, v65, v71
	v_add_f32_e32 v39, v39, v40
	v_add_f32_e32 v38, v38, v39
	v_add_f32_e32 v73, v58, v38
	v_mul_f32_e32 v38, v60, v60
	v_mul_f32_e32 v39, v62, v62
	v_fmac_f32_e32 v38, v59, v59
	v_fmac_f32_e32 v39, v61, v61
	v_add_f32_e32 v38, v38, v39
	v_mul_f32_e32 v39, v64, v64
	v_mul_f32_e32 v40, v71, v71
	v_fmac_f32_e32 v39, v63, v63
	v_fmac_f32_e32 v40, v65, v65
	v_add_f32_e32 v39, v39, v40
	v_add_f32_e32 v38, v38, v39
	v_lshlrev_b32_e32 v58, 16, v34
	v_and_b32_e32 v41, 0xffff0000, v34
	v_lshlrev_b32_e32 v40, 16, v35
	v_and_b32_e32 v39, 0xffff0000, v35
	v_add_f32_e32 v72, v72, v38
	v_lshlrev_b32_e32 v38, 16, v36
	v_and_b32_e32 v36, 0xffff0000, v36
	v_lshlrev_b32_e32 v35, 16, v37
	v_and_b32_e32 v34, 0xffff0000, v37
	v_add_f32_e32 v37, v58, v41
	v_add_f32_e32 v74, v40, v39
	v_add_f32_e32 v37, v37, v74
	v_add_f32_e32 v74, v38, v36
	v_add_f32_e32 v75, v35, v34
	v_add_f32_e32 v74, v74, v75
	v_add_f32_e32 v37, v37, v74
	v_add_f32_e32 v37, v73, v37
	v_mul_f32_e32 v73, v41, v41
	v_mul_f32_e32 v74, v39, v39
	v_fmac_f32_e32 v73, v58, v58
	v_fmac_f32_e32 v74, v40, v40
	v_add_f32_e32 v73, v73, v74
	v_mul_f32_e32 v74, v36, v36
	v_mul_f32_e32 v75, v34, v34
	v_fmac_f32_e32 v74, v38, v38
	v_fmac_f32_e32 v75, v35, v35
	v_add_f32_e32 v74, v74, v75
	v_add_f32_e32 v73, v73, v74
	v_add_f32_e32 v72, v72, v73
	s_nop 1
	v_mov_b32_dpp v73, v37 quad_perm:[1,0,3,2] row_mask:0xf bank_mask:0xf
	s_cmp_lt_i32 s65, 2
	s_mov_b64 s[10:11], -1
	s_waitcnt lgkmcnt(0)
	v_add_f32_e32 v37, v37, v73
	s_nop 1
	v_mov_b32_dpp v73, v72 quad_perm:[1,0,3,2] row_mask:0xf bank_mask:0xf
	s_waitcnt lgkmcnt(0)
	v_add_f32_e32 v72, v72, v73
	s_nop 1
	v_mov_b32_dpp v73, v37 quad_perm:[2,3,0,1] row_mask:0xf bank_mask:0xf
	s_waitcnt lgkmcnt(0)
	v_add_f32_e32 v37, v37, v73
	s_nop 1
	v_mov_b32_dpp v73, v72 quad_perm:[2,3,0,1] row_mask:0xf bank_mask:0xf
	s_waitcnt lgkmcnt(0)
	v_add_f32_e32 v72, v72, v73
	s_nop 1
	v_mov_b32_dpp v73, v37 row_half_mirror row_mask:0xf bank_mask:0xf
	s_waitcnt lgkmcnt(0)
	v_add_f32_e32 v37, v37, v73
	s_nop 1
	v_mov_b32_dpp v73, v72 row_half_mirror row_mask:0xf bank_mask:0xf
	s_waitcnt lgkmcnt(0)
	v_add_f32_e32 v72, v72, v73
	s_nop 1
	v_mov_b32_dpp v73, v37 row_mirror row_mask:0xf bank_mask:0xf
	s_nop 1
	v_mov_b32_dpp v74, v72 row_mirror row_mask:0xf bank_mask:0xf
	s_cbranch_scc1 .LBB0_1201
	s_cmp_lt_i32 s65, 3
	s_cbranch_scc0 .LBB0_1200
	v_mov_b32_e32 v58, v59
	v_mov_b32_e32 v41, v60
	v_mov_b32_e32 v40, v61
	v_mov_b32_e32 v39, v62
	v_mov_b32_e32 v38, v63
	v_mov_b32_e32 v36, v64
	v_mov_b32_e32 v35, v65
	v_mov_b32_e32 v34, v71

.LBB0_1207:
	s_waitcnt lgkmcnt(1)
	v_add_f32_e32 v37, v37, v73
	v_mul_f32_e32 v43, 0x3b000000, v37
	s_waitcnt lgkmcnt(0)
	v_add_f32_e32 v42, v72, v74
	v_mul_f32_e32 v43, v43, v43
	v_fma_f32 v42, v42, s73, -v43
	v_max_f32_e32 v42, 0, v42
	v_add_f32_e32 v42, 0x358637bd, v42
	v_fmac_f32_e32 v35, 0xbb000000, v37
	v_rsq_f32_e32 v43, v42
	v_fmac_f32_e32 v34, 0xbb000000, v37
	v_fmac_f32_e32 v39, 0xbb000000, v37
	v_fmac_f32_e32 v38, 0xbb000000, v37
	v_fmac_f32_e32 v36, 0xbb000000, v37
	v_fmac_f32_e32 v58, 0xbb000000, v37
	v_fmac_f32_e32 v41, 0xbb000000, v37
	v_fmac_f32_e32 v40, 0xbb000000, v37
	v_lshlrev_b32_e32 v37, 16, v31
	v_and_b32_e32 v31, 0xffff0000, v31
	v_and_b32_e32 v48, 0xffff0000, v22
	v_lshlrev_b32_e32 v49, 16, v23
	s_nop 0
	v_mov_b32_e32 v45, v43
	v_mul_f32_e32 v35, v45, v35
	v_mul_f32_e32 v34, v45, v34
	v_mul_f32_e32 v39, v45, v39
	v_mul_f32_e32 v38, v45, v38
	v_mul_f32_e32 v36, v45, v36
	v_fma_f32 v35, v2, v35, v6
	v_fma_f32 v34, v3, v34, v7
	v_mul_f32_e32 v42, v45, v58
	v_mul_f32_e32 v41, v45, v41
	v_mul_f32_e32 v40, v45, v40
	v_fma_f32 v39, v11, v39, v15
	v_fma_f32 v38, v0, v38, v4
	v_fma_f32 v36, v1, v36, v5
	v_cvt_pk_bf16_f32 v45, v35, v34
	v_lshlrev_b32_e32 v34, 16, v28
	v_and_b32_e32 v28, 0xffff0000, v28
	v_lshlrev_b32_e32 v35, 16, v29
	v_and_b32_e32 v29, 0xffff0000, v29
	v_fma_f32 v40, v10, v40, v14
	v_cvt_pk_bf16_f32 v43, v40, v39
	v_cvt_pk_bf16_f32 v44, v38, v36
	v_lshlrev_b32_e32 v36, 16, v30
	v_and_b32_e32 v30, 0xffff0000, v30
	v_add_f32_e32 v38, v34, v28
	v_add_f32_e32 v39, v35, v29
	v_add_f32_e32 v38, v38, v39
	v_add_f32_e32 v39, v36, v30
	v_add_f32_e32 v40, v37, v31
	v_fma_f32 v42, v8, v42, v12
	v_add_f32_e32 v39, v39, v40
	v_fma_f32 v41, v9, v41, v13
	v_cvt_pk_bf16_f32 v42, v42, v41
	v_add_f32_e32 v38, v38, v39
	ds_write_b128 v70, v[42:45] offset:2304
	v_add_f32_e32 v42, 0, v38
	v_mul_f32_e32 v38, v28, v28
	v_mul_f32_e32 v39, v29, v29
	v_fmac_f32_e32 v38, v34, v34
	v_fmac_f32_e32 v39, v35, v35
	v_add_f32_e32 v38, v38, v39
	v_mul_f32_e32 v39, v30, v30
	v_mul_f32_e32 v40, v31, v31
	v_fmac_f32_e32 v39, v36, v36
	v_fmac_f32_e32 v40, v37, v37
	v_add_f32_e32 v39, v39, v40
	v_add_f32_e32 v43, v38, v39
	v_lshlrev_b32_e32 v38, 16, v24
	v_and_b32_e32 v24, 0xffff0000, v24
	v_lshlrev_b32_e32 v39, 16, v25
	v_and_b32_e32 v25, 0xffff0000, v25
	v_lshlrev_b32_e32 v40, 16, v26
	v_and_b32_e32 v26, 0xffff0000, v26
	v_lshlrev_b32_e32 v41, 16, v27
	v_and_b32_e32 v27, 0xffff0000, v27
	v_add_f32_e32 v44, v38, v24
	v_add_f32_e32 v45, v39, v25
	v_add_f32_e32 v44, v44, v45
	v_add_f32_e32 v45, v40, v26
	v_add_f32_e32 v46, v41, v27
	v_add_f32_e32 v45, v45, v46
	v_add_f32_e32 v44, v44, v45
	v_add_f32_e32 v51, v42, v44
	v_mul_f32_e32 v42, v24, v24
	v_mul_f32_e32 v44, v25, v25
	v_fmac_f32_e32 v42, v38, v38
	v_fmac_f32_e32 v44, v39, v39
	v_add_f32_e32 v42, v42, v44
	v_mul_f32_e32 v44, v26, v26
	v_mul_f32_e32 v45, v27, v27
	v_fmac_f32_e32 v44, v40, v40
	v_fmac_f32_e32 v45, v41, v41
	v_add_f32_e32 v44, v44, v45
	v_add_f32_e32 v42, v42, v44
	v_add_f32_e32 v43, v43, v42
	v_lshlrev_b32_e32 v42, 16, v20
	v_and_b32_e32 v44, 0xffff0000, v20
	v_lshlrev_b32_e32 v45, 16, v21
	v_and_b32_e32 v46, 0xffff0000, v21
	v_lshlrev_b32_e32 v47, 16, v22
	v_and_b32_e32 v50, 0xffff0000, v23
	v_add_f32_e32 v20, v42, v44
	v_add_f32_e32 v21, v45, v46
	v_add_f32_e32 v20, v20, v21
	v_add_f32_e32 v21, v47, v48
	v_add_f32_e32 v22, v49, v50
	v_add_f32_e32 v21, v21, v22
	v_add_f32_e32 v20, v20, v21
	v_add_f32_e32 v51, v51, v20
	v_mul_f32_e32 v20, v44, v44
	v_mul_f32_e32 v21, v46, v46
	v_fmac_f32_e32 v20, v42, v42
	v_fmac_f32_e32 v21, v45, v45
	v_add_f32_e32 v20, v20, v21
	v_mul_f32_e32 v21, v48, v48
	v_mul_f32_e32 v22, v50, v50
	v_fmac_f32_e32 v21, v47, v47
	v_fmac_f32_e32 v22, v49, v49
	v_add_f32_e32 v21, v21, v22
	v_add_f32_e32 v20, v20, v21
	v_add_f32_e32 v52, v43, v20
	v_lshlrev_b32_e32 v43, 16, v16
	v_and_b32_e32 v23, 0xffff0000, v16
	v_lshlrev_b32_e32 v22, 16, v17
	v_and_b32_e32 v21, 0xffff0000, v17
	v_lshlrev_b32_e32 v20, 16, v18
	v_and_b32_e32 v18, 0xffff0000, v18
	v_lshlrev_b32_e32 v17, 16, v19
	v_and_b32_e32 v16, 0xffff0000, v19
	v_add_f32_e32 v19, v43, v23
	v_add_f32_e32 v53, v22, v21
	v_add_f32_e32 v19, v19, v53
	v_add_f32_e32 v53, v20, v18
	v_add_f32_e32 v54, v17, v16
	v_add_f32_e32 v53, v53, v54
	v_add_f32_e32 v19, v19, v53
	v_add_f32_e32 v19, v51, v19
	v_mul_f32_e32 v51, v23, v23
	v_mul_f32_e32 v53, v21, v21
	v_fmac_f32_e32 v51, v43, v43
	v_fmac_f32_e32 v53, v22, v22
	v_add_f32_e32 v51, v51, v53
	v_mul_f32_e32 v53, v18, v18
	v_mul_f32_e32 v54, v16, v16
	v_fmac_f32_e32 v53, v20, v20
	v_fmac_f32_e32 v54, v17, v17
	v_add_f32_e32 v53, v53, v54
	v_add_f32_e32 v51, v51, v53
	v_add_f32_e32 v51, v52, v51
	s_nop 1
	v_mov_b32_dpp v52, v19 quad_perm:[1,0,3,2] row_mask:0xf bank_mask:0xf
	s_cmp_lt_i32 s65, 2
	s_mov_b64 s[10:11], -1
	s_waitcnt lgkmcnt(0)
	v_add_f32_e32 v19, v19, v52
	s_nop 1
	v_mov_b32_dpp v52, v51 quad_perm:[1,0,3,2] row_mask:0xf bank_mask:0xf
	s_waitcnt lgkmcnt(0)
	v_add_f32_e32 v51, v51, v52
	s_nop 1
	v_mov_b32_dpp v52, v19 quad_perm:[2,3,0,1] row_mask:0xf bank_mask:0xf
	s_waitcnt lgkmcnt(0)
	v_add_f32_e32 v19, v19, v52
	s_nop 1
	v_mov_b32_dpp v52, v51 quad_perm:[2,3,0,1] row_mask:0xf bank_mask:0xf
	s_waitcnt lgkmcnt(0)
	v_add_f32_e32 v51, v51, v52
	s_nop 1
	v_mov_b32_dpp v52, v19 row_half_mirror row_mask:0xf bank_mask:0xf
	s_waitcnt lgkmcnt(0)
	v_add_f32_e32 v19, v19, v52
	s_nop 1
	v_mov_b32_dpp v52, v51 row_half_mirror row_mask:0xf bank_mask:0xf
	s_waitcnt lgkmcnt(0)
	v_add_f32_e32 v51, v51, v52
	s_nop 1
	v_mov_b32_dpp v52, v19 row_mirror row_mask:0xf bank_mask:0xf
	s_nop 1
	v_mov_b32_dpp v32, v51 row_mirror row_mask:0xf bank_mask:0xf
	s_cbranch_scc1 .LBB0_1211
	s_cmp_lt_i32 s65, 3
	s_cbranch_scc0 .LBB0_1210
	v_mov_b32_e32 v43, v42
	v_mov_b32_e32 v23, v44
	v_mov_b32_e32 v22, v45
	v_mov_b32_e32 v21, v46
	v_mov_b32_e32 v20, v47
	v_mov_b32_e32 v18, v48
	v_mov_b32_e32 v17, v49
	v_mov_b32_e32 v16, v50

.LBB0_1217:
	s_waitcnt lgkmcnt(1)
	v_add_f32_e32 v19, v19, v52
	v_mul_f32_e32 v25, 0x3b000000, v19
	s_waitcnt lgkmcnt(0)
	v_add_f32_e32 v24, v51, v32
	v_mul_f32_e32 v25, v25, v25
	v_fma_f32 v24, v24, s73, -v25
	v_max_f32_e32 v24, 0, v24
	v_add_f32_e32 v24, 0x358637bd, v24
	v_fmac_f32_e32 v43, 0xbb000000, v19
	v_rsq_f32_e32 v25, v24
	v_fmac_f32_e32 v23, 0xbb000000, v19
	v_fmac_f32_e32 v22, 0xbb000000, v19
	v_fmac_f32_e32 v21, 0xbb000000, v19
	v_fmac_f32_e32 v20, 0xbb000000, v19
	v_fmac_f32_e32 v18, 0xbb000000, v19
	v_fmac_f32_e32 v17, 0xbb000000, v19
	v_fmac_f32_e32 v16, 0xbb000000, v19
	v_lshlrev_b32_e32 v32, 3, v66
	v_readlane_b32 s48, v252, 36
	v_readlane_b32 s62, v252, 50
	v_readlane_b32 s63, v252, 51
	s_nop 0
	v_mov_b32_e32 v24, v25
	v_mul_f32_e32 v25, v24, v43
	v_fma_f32 v8, v8, v25, v12
	v_mul_f32_e32 v12, v24, v23
	v_fma_f32 v9, v9, v12, v13
	v_cvt_pk_bf16_f32 v8, v8, v9
	v_mul_f32_e32 v9, v24, v22
	v_fma_f32 v9, v10, v9, v14
	v_mul_f32_e32 v10, v24, v21
	v_fmac_f32_e32 v15, v11, v10
	v_mul_f32_e32 v10, v24, v20
	v_fma_f32 v0, v0, v10, v4
	v_mul_f32_e32 v4, v24, v18
	v_fma_f32 v1, v1, v4, v5
	v_cvt_pk_bf16_f32 v10, v0, v1
	v_mul_f32_e32 v0, v24, v17
	v_mul_f32_e32 v1, v24, v16
	v_or_b32_e32 v4, s31, v89
	v_fma_f32 v0, v2, v0, v6
	v_fmac_f32_e32 v7, v3, v1
	v_ashrrev_i32_e32 v5, 31, v4
	v_cvt_pk_bf16_f32 v11, v0, v7
	v_lshlrev_b64 v[0:1], 8, v[4:5]
	v_add_u32_e32 v5, s30, v4
	v_mov_b64_e32 v[6:7], s[34:35]
	v_lshl_add_u64 v[0:1], s[18:19], 0, v[0:1]
	v_lshlrev_b32_e32 v2, 4, v66
	v_mov_b32_e32 v3, v33
	v_mad_i64_i32 v[6:7], s[8:9], v5, s70, v[6:7]
	v_cvt_pk_bf16_f32 v9, v9, v15
	ds_write_b128 v70, v[8:11] offset:3456
	v_lshl_add_u64 v[0:1], v[0:1], 0, v[2:3]
	v_lshl_add_u64 v[54:55], v[6:7], 0, v[32:33]
	s_nop 0
	s_nop 0
	v_add_u32_e32 v4, s2, v4
	v_ashrrev_i32_e32 v5, 31, v4
	v_lshl_add_u64 v[4:5], v[4:5], 2, s[62:63]
	s_waitcnt vmcnt(0)
	v_mov_b64_e32 v[50:51], v[140:141]
	v_mov_b64_e32 v[52:53], v[142:143]
	v_mov_b64_e32 v[46:47], v[144:145]
	v_mov_b64_e32 v[48:49], v[146:147]
	v_mov_b64_e32 v[38:39], v[148:149]
	v_mov_b64_e32 v[40:41], v[150:151]
	v_mov_b64_e32 v[0:1], v[152:153]
	v_mov_b64_e32 v[2:3], v[154:155]
	v_mov_b64_e32 v[86:87], v[164:165]
	v_mov_b64_e32 v[84:85], v[166:167]
	v_mov_b64_e32 v[82:83], v[168:169]
	v_mov_b64_e32 v[80:81], v[170:171]
	v_mov_b64_e32 v[78:79], v[172:173]
	v_mov_b64_e32 v[76:77], v[174:175]
	v_mov_b64_e32 v[72:73], v[176:177]
	v_mov_b64_e32 v[74:75], v[178:179]
	v_mov_b64_e32 v[70:71], v[180:181]
	v_mov_b64_e32 v[68:69], v[182:183]
	v_mov_b64_e32 v[66:67], v[184:185]
	v_mov_b64_e32 v[64:65], v[186:187]
	v_mov_b64_e32 v[62:63], v[188:189]
	v_mov_b64_e32 v[60:61], v[190:191]
	v_mov_b64_e32 v[56:57], v[192:193]
	v_mov_b64_e32 v[58:59], v[194:195]
	v_mov_b32_e32 v90, v156
	v_lshrrev_b32_e32 v4, 2, v89
	v_or_b32_e32 v4, v32, v4
	v_lshlrev_b32_e32 v5, 3, v88
	v_mov_b32_e32 v42, 0
	s_ashr_i32 s8, s28, 7
	v_mul_u32_u24_e32 v4, 0x120, v4
	v_and_b32_e32 v5, 24, v5
	v_add3_u32 v32, 0, v4, v5
	s_cmp_lt_i32 s8, 0
	v_mov_b32_e32 v43, 0
	v_mov_b32_e32 v44, 0
	v_mov_b32_e32 v45, 0
	v_mov_b32_e32 v28, 0
	v_mov_b32_e32 v29, v42
	v_mov_b32_e32 v30, v42
	v_mov_b32_e32 v31, v42
	v_mov_b32_e32 v24, v42
	v_mov_b32_e32 v25, v42
	v_mov_b32_e32 v26, v42
	v_mov_b32_e32 v27, v42
	v_mov_b32_e32 v20, v42
	v_mov_b32_e32 v21, v42
	v_mov_b32_e32 v22, v42
	v_mov_b32_e32 v23, v42
	v_mov_b32_e32 v16, v42
	v_mov_b32_e32 v17, v42
	v_mov_b32_e32 v18, v42
	v_mov_b32_e32 v19, v42
	v_mov_b32_e32 v12, v42
	v_mov_b32_e32 v13, v42
	v_mov_b32_e32 v14, v42
	v_mov_b32_e32 v15, v42
	v_mov_b32_e32 v8, v42
	v_mov_b32_e32 v9, v42
	v_mov_b32_e32 v10, v42
	v_mov_b32_e32 v11, v42
	v_mov_b32_e32 v4, v42
	v_mov_b32_e32 v5, v42
	v_mov_b32_e32 v6, v42
	v_mov_b32_e32 v7, v42
	v_mov_b32_e32 v34, v42
	v_mov_b32_e32 v35, v42
	v_mov_b32_e32 v36, v42
	v_mov_b32_e32 v37, v42
	v_readlane_b32 s49, v252, 37
	v_readlane_b32 s50, v252, 38
	v_readlane_b32 s51, v252, 39
	v_readlane_b32 s52, v252, 40
	v_readlane_b32 s53, v252, 41
	v_readlane_b32 s54, v252, 42
	v_readlane_b32 s55, v252, 43
	v_readlane_b32 s56, v252, 44
	v_readlane_b32 s57, v252, 45
	v_readlane_b32 s58, v252, 46
	v_readlane_b32 s59, v252, 47
	v_readlane_b32 s60, v252, 48
	v_readlane_b32 s61, v252, 49
	s_waitcnt lgkmcnt(0)
	s_barrier
	s_cbranch_scc0 .LBB0_1221
	s_cmp_lt_i32 s8, 1
	s_cbranch_scc0 .LBB0_1222

.Lpf_ret_k3:
	global_load_dwordx2 v[96:97], v[94:95], off
	global_load_dwordx2 v[92:93], v[78:79], off offset:32
	global_load_dwordx2 v[90:91], v[78:79], off offset:64
	global_load_dwordx2 v[88:89], v[78:79], off offset:96
	global_load_dwordx2 v[86:87], v[78:79], off offset:128
	global_load_dwordx2 v[84:85], v[78:79], off offset:160
	global_load_dwordx2 v[82:83], v[78:79], off offset:192
	global_load_dwordx2 v[80:81], v[78:79], off offset:224
	v_add_u32_e32 v32, 0, v106
	v_mad_u32_u24 v126, v108, s33, v32
	ds_read_b128 v[4:7], v126
	ds_read_b128 v[8:11], v126 offset:64
	ds_read_b128 v[12:15], v126 offset:128
	ds_read_b128 v[16:19], v126 offset:192
	ds_read_b128 v[20:23], v126 offset:4352
	ds_read_b128 v[24:27], v126 offset:4416
	ds_read_b128 v[28:31], v126 offset:4480
	ds_read_b128 v[34:37], v126 offset:4544
	s_waitcnt lgkmcnt(7)
	v_mfma_f32_16x16x32_bf16 v[4:7], v[4:7], v[0:3], 0
	s_waitcnt lgkmcnt(6)
	v_mfma_f32_16x16x32_bf16 v[4:7], v[8:11], v[62:65], v[4:7]
	s_waitcnt lgkmcnt(5)
	v_mfma_f32_16x16x32_bf16 v[4:7], v[12:15], v[66:69], v[4:7]
	s_waitcnt lgkmcnt(4)
	v_mfma_f32_16x16x32_bf16 v[74:77], v[16:19], v[70:73], v[4:7]
	s_waitcnt lgkmcnt(3)
	v_mfma_f32_16x16x32_bf16 v[4:7], v[20:23], v[0:3], 0
	s_waitcnt lgkmcnt(2)
	v_mfma_f32_16x16x32_bf16 v[4:7], v[24:27], v[62:65], v[4:7]
	s_waitcnt lgkmcnt(1)
	v_mfma_f32_16x16x32_bf16 v[4:7], v[28:31], v[66:69], v[4:7]
	s_waitcnt lgkmcnt(0)
	v_mfma_f32_16x16x32_bf16 v[58:61], v[34:37], v[70:73], v[4:7]
	v_or_b32_e32 v20, 48, v98
	v_mad_u32_u24 v34, v20, s33, v32
	s_nop 3
	ds_read_b128 v[4:7], v126 offset:8704
	ds_read_b128 v[8:11], v126 offset:8768
	ds_read_b128 v[12:15], v126 offset:8832
	ds_read_b128 v[16:19], v126 offset:8896
	ds_read_b128 v[20:23], v34
	ds_read_b128 v[24:27], v34 offset:64
	ds_read_b128 v[28:31], v34 offset:128
	ds_read_b128 v[34:37], v34 offset:192
	s_waitcnt lgkmcnt(7)
	v_mfma_f32_16x16x32_bf16 v[4:7], v[4:7], v[0:3], 0
	s_waitcnt lgkmcnt(6)
	v_mfma_f32_16x16x32_bf16 v[4:7], v[8:11], v[62:65], v[4:7]
	s_waitcnt lgkmcnt(5)
	v_mfma_f32_16x16x32_bf16 v[4:7], v[12:15], v[66:69], v[4:7]
	s_waitcnt lgkmcnt(4)
	v_mfma_f32_16x16x32_bf16 v[54:57], v[16:19], v[70:73], v[4:7]
	s_waitcnt lgkmcnt(3)
	v_mfma_f32_16x16x32_bf16 v[4:7], v[20:23], v[0:3], 0
	s_waitcnt lgkmcnt(2)
	v_mfma_f32_16x16x32_bf16 v[4:7], v[24:27], v[62:65], v[4:7]
	s_waitcnt lgkmcnt(1)
	v_mfma_f32_16x16x32_bf16 v[4:7], v[28:31], v[66:69], v[4:7]
	s_waitcnt lgkmcnt(0)
	v_mfma_f32_16x16x32_bf16 v[50:53], v[34:37], v[70:73], v[4:7]
	s_nop 5
	ds_read_b128 v[4:7], v126 offset:17408
	ds_read_b128 v[8:11], v126 offset:17472
	ds_read_b128 v[12:15], v126 offset:17536
	ds_read_b128 v[16:19], v126 offset:17600
	ds_read_b128 v[20:23], v126 offset:21760
	ds_read_b128 v[24:27], v126 offset:21824
	ds_read_b128 v[28:31], v126 offset:21888
	ds_read_b128 v[34:37], v126 offset:21952
	s_waitcnt lgkmcnt(7)
	v_mfma_f32_16x16x32_bf16 v[4:7], v[4:7], v[0:3], 0
	s_waitcnt lgkmcnt(6)
	v_mfma_f32_16x16x32_bf16 v[4:7], v[8:11], v[62:65], v[4:7]
	s_waitcnt lgkmcnt(5)
	v_mfma_f32_16x16x32_bf16 v[4:7], v[12:15], v[66:69], v[4:7]
	s_waitcnt lgkmcnt(4)
	v_mfma_f32_16x16x32_bf16 v[46:49], v[16:19], v[70:73], v[4:7]
	s_waitcnt lgkmcnt(3)
	v_mfma_f32_16x16x32_bf16 v[4:7], v[20:23], v[0:3], 0
	s_waitcnt lgkmcnt(2)
	v_mfma_f32_16x16x32_bf16 v[4:7], v[24:27], v[62:65], v[4:7]
	s_waitcnt lgkmcnt(1)
	v_mfma_f32_16x16x32_bf16 v[4:7], v[28:31], v[66:69], v[4:7]
	s_waitcnt lgkmcnt(0)
	v_mfma_f32_16x16x32_bf16 v[42:45], v[34:37], v[70:73], v[4:7]
	v_or_b32_e32 v20, 0x70, v98
	v_mad_u32_u24 v34, v20, s33, v32
	s_nop 3
	ds_read_b128 v[4:7], v126 offset:26112
	ds_read_b128 v[8:11], v126 offset:26176
	ds_read_b128 v[12:15], v126 offset:26240
	ds_read_b128 v[16:19], v126 offset:26304
	ds_read_b128 v[20:23], v34
	ds_read_b128 v[24:27], v34 offset:64
	ds_read_b128 v[28:31], v34 offset:128
	ds_read_b128 v[34:37], v34 offset:192
	s_waitcnt lgkmcnt(7)
	v_mfma_f32_16x16x32_bf16 v[4:7], v[4:7], v[0:3], 0
	s_waitcnt lgkmcnt(6)
	v_mfma_f32_16x16x32_bf16 v[4:7], v[8:11], v[62:65], v[4:7]
	s_waitcnt lgkmcnt(5)
	v_mfma_f32_16x16x32_bf16 v[4:7], v[12:15], v[66:69], v[4:7]
	s_waitcnt lgkmcnt(4)
	v_mfma_f32_16x16x32_bf16 v[38:41], v[16:19], v[70:73], v[4:7]
	s_waitcnt lgkmcnt(3)
	v_mfma_f32_16x16x32_bf16 v[4:7], v[20:23], v[0:3], 0
	s_waitcnt lgkmcnt(2)
	v_mfma_f32_16x16x32_bf16 v[4:7], v[24:27], v[62:65], v[4:7]
	s_waitcnt lgkmcnt(1)
	v_mfma_f32_16x16x32_bf16 v[4:7], v[28:31], v[66:69], v[4:7]
	s_waitcnt lgkmcnt(0)
	v_mfma_f32_16x16x32_bf16 v[34:37], v[34:37], v[70:73], v[4:7]
	s_nop 5
	ds_read_b128 v[4:7], v126 offset:34816
	ds_read_b128 v[8:11], v126 offset:34880
	ds_read_b128 v[12:15], v126 offset:34944
	ds_read_b128 v[16:19], v126 offset:35008
	ds_read_b128 v[20:23], v126 offset:39168
	ds_read_b128 v[24:27], v126 offset:39232
	ds_read_b128 v[106:109], v126 offset:39296
	ds_read_b128 v[110:113], v126 offset:39360
	s_waitcnt lgkmcnt(7)
	v_mfma_f32_16x16x32_bf16 v[4:7], v[4:7], v[0:3], 0
	s_waitcnt lgkmcnt(6)
	v_mfma_f32_16x16x32_bf16 v[4:7], v[8:11], v[62:65], v[4:7]
	s_waitcnt lgkmcnt(5)
	v_mfma_f32_16x16x32_bf16 v[4:7], v[12:15], v[66:69], v[4:7]
	s_waitcnt lgkmcnt(4)
	v_mfma_f32_16x16x32_bf16 v[28:31], v[16:19], v[70:73], v[4:7]
	s_waitcnt lgkmcnt(3)
	v_mfma_f32_16x16x32_bf16 v[4:7], v[20:23], v[0:3], 0
	s_waitcnt lgkmcnt(2)
	v_mfma_f32_16x16x32_bf16 v[4:7], v[24:27], v[62:65], v[4:7]
	s_waitcnt lgkmcnt(1)
	v_mfma_f32_16x16x32_bf16 v[4:7], v[106:109], v[66:69], v[4:7]
	s_waitcnt lgkmcnt(0)
	v_mfma_f32_16x16x32_bf16 v[24:27], v[110:113], v[70:73], v[4:7]
	v_or_b32_e32 v20, 0xb0, v98
	v_mad_u32_u24 v20, v20, s33, v32
	s_nop 3
	ds_read_b128 v[4:7], v126 offset:43520
	ds_read_b128 v[8:11], v126 offset:43584
	ds_read_b128 v[12:15], v126 offset:43648
	ds_read_b128 v[16:19], v126 offset:43712
	ds_read_b128 v[106:109], v20
	ds_read_b128 v[110:113], v20 offset:64
	ds_read_b128 v[114:117], v20 offset:128
	ds_read_b128 v[118:121], v20 offset:192
	s_waitcnt lgkmcnt(7)
	v_mfma_f32_16x16x32_bf16 v[4:7], v[4:7], v[0:3], 0
	s_waitcnt lgkmcnt(6)
	v_mfma_f32_16x16x32_bf16 v[4:7], v[8:11], v[62:65], v[4:7]
	s_waitcnt lgkmcnt(5)
	v_mfma_f32_16x16x32_bf16 v[4:7], v[12:15], v[66:69], v[4:7]
	s_waitcnt lgkmcnt(4)
	v_mfma_f32_16x16x32_bf16 v[20:23], v[16:19], v[70:73], v[4:7]
	s_waitcnt lgkmcnt(3)
	v_mfma_f32_16x16x32_bf16 v[4:7], v[106:109], v[0:3], 0
	s_waitcnt lgkmcnt(2)
	v_mfma_f32_16x16x32_bf16 v[4:7], v[110:113], v[62:65], v[4:7]
	s_waitcnt lgkmcnt(1)
	v_mfma_f32_16x16x32_bf16 v[4:7], v[114:117], v[66:69], v[4:7]
	s_waitcnt lgkmcnt(0)
	v_mfma_f32_16x16x32_bf16 v[16:19], v[118:121], v[70:73], v[4:7]
	s_nop 5
	ds_read_b128 v[4:7], v126 offset:52224
	ds_read_b128 v[8:11], v126 offset:52288
	ds_read_b128 v[12:15], v126 offset:52352
	ds_read_b128 v[106:109], v126 offset:52416
	ds_read_b128 v[110:113], v126 offset:56576
	ds_read_b128 v[114:117], v126 offset:56640
	ds_read_b128 v[118:121], v126 offset:56704
	ds_read_b128 v[122:125], v126 offset:56768
	s_waitcnt lgkmcnt(7)
	v_mfma_f32_16x16x32_bf16 v[4:7], v[4:7], v[0:3], 0
	s_waitcnt lgkmcnt(6)
	v_mfma_f32_16x16x32_bf16 v[4:7], v[8:11], v[62:65], v[4:7]
	s_waitcnt lgkmcnt(5)
	v_mfma_f32_16x16x32_bf16 v[4:7], v[12:15], v[66:69], v[4:7]
	s_waitcnt lgkmcnt(4)
	v_mfma_f32_16x16x32_bf16 v[12:15], v[106:109], v[70:73], v[4:7]
	s_waitcnt lgkmcnt(3)
	v_mfma_f32_16x16x32_bf16 v[4:7], v[110:113], v[0:3], 0
	s_waitcnt lgkmcnt(2)
	v_mfma_f32_16x16x32_bf16 v[4:7], v[114:117], v[62:65], v[4:7]
	s_waitcnt lgkmcnt(1)
	v_mfma_f32_16x16x32_bf16 v[4:7], v[118:121], v[66:69], v[4:7]
	s_waitcnt lgkmcnt(0)
	v_mfma_f32_16x16x32_bf16 v[8:11], v[122:125], v[70:73], v[4:7]
	v_or_b32_e32 v118, 0xf0, v98
	v_mad_u32_u24 v32, v118, s33, v32
	s_nop 3
	ds_read_b128 v[4:7], v126 offset:60928
	ds_read_b128 v[106:109], v126 offset:60992
	ds_read_b128 v[110:113], v126 offset:61056
	ds_read_b128 v[114:117], v126 offset:61120
	ds_read_b128 v[118:121], v32
	ds_read_b128 v[122:125], v32 offset:64
	ds_read_b128 v[126:129], v32 offset:128
	ds_read_b128 v[130:133], v32 offset:192
	s_waitcnt lgkmcnt(7)
	v_mfma_f32_16x16x32_bf16 v[4:7], v[4:7], v[0:3], 0
	s_waitcnt lgkmcnt(3)
	v_mfma_f32_16x16x32_bf16 v[0:3], v[118:121], v[0:3], 0
	v_mfma_f32_16x16x32_bf16 v[4:7], v[106:109], v[62:65], v[4:7]
	s_waitcnt lgkmcnt(2)
	v_mfma_f32_16x16x32_bf16 v[0:3], v[122:125], v[62:65], v[0:3]
	v_mfma_f32_16x16x32_bf16 v[4:7], v[110:113], v[66:69], v[4:7]
	s_waitcnt lgkmcnt(1)
	v_mfma_f32_16x16x32_bf16 v[0:3], v[126:129], v[66:69], v[0:3]
	v_mfma_f32_16x16x32_bf16 v[4:7], v[114:117], v[70:73], v[4:7]
	s_waitcnt lgkmcnt(0)
	v_mfma_f32_16x16x32_bf16 v[0:3], v[130:133], v[70:73], v[0:3]
	v_max_f32_e32 v32, v74, v75
	v_max_f32_e32 v62, v76, v77
	s_mov_b32 s8, 0xff61b1e6
	v_max3_f32 v32, v32, v62, s8
	v_max_f32_e32 v62, v58, v59
	v_max_f32_e32 v63, v60, v61
	v_max3_f32 v32, v62, v63, v32
	v_max_f32_e32 v62, v54, v55
	v_max_f32_e32 v63, v56, v57
	v_max3_f32 v32, v62, v63, v32
	v_max_f32_e32 v62, v50, v51
	v_max_f32_e32 v63, v52, v53
	v_max3_f32 v32, v62, v63, v32
	v_max_f32_e32 v62, v46, v47
	v_max_f32_e32 v63, v48, v49
	v_max3_f32 v32, v62, v63, v32
	v_max_f32_e32 v62, v42, v43
	v_max_f32_e32 v63, v44, v45
	v_max3_f32 v32, v62, v63, v32
	v_max_f32_e32 v62, v38, v39
	v_max_f32_e32 v63, v40, v41
	v_max3_f32 v32, v62, v63, v32
	v_max_f32_e32 v62, v34, v35
	v_max_f32_e32 v63, v36, v37
	v_max3_f32 v32, v62, v63, v32
	v_max_f32_e32 v62, v28, v29
	v_max_f32_e32 v63, v30, v31
	v_max3_f32 v32, v62, v63, v32
	v_max_f32_e32 v62, v24, v25
	v_max_f32_e32 v63, v26, v27
	v_max3_f32 v32, v62, v63, v32
	v_max_f32_e32 v62, v20, v21
	v_max_f32_e32 v63, v22, v23
	v_max3_f32 v32, v62, v63, v32
	v_max_f32_e32 v62, v16, v17
	v_max_f32_e32 v63, v18, v19
	v_max3_f32 v32, v62, v63, v32
	v_max_f32_e32 v62, v12, v13
	v_max_f32_e32 v63, v14, v15
	v_max3_f32 v32, v62, v63, v32
	v_max_f32_e32 v62, v8, v9
	v_max_f32_e32 v63, v10, v11
	v_max3_f32 v32, v62, v63, v32
	v_max_f32_e32 v62, v4, v5
	v_max_f32_e32 v63, v6, v7
	v_max3_f32 v32, v62, v63, v32
	v_max_f32_e32 v62, v0, v1
	v_max_f32_e32 v63, v2, v3
	v_max3_f32 v32, v62, v63, v32
	ds_bpermute_b32 v62, v100, v32
	s_waitcnt lgkmcnt(0)
	v_max_f32_e32 v32, v32, v62
	ds_bpermute_b32 v62, v101, v32
	s_waitcnt lgkmcnt(0)
	v_max_f32_e32 v66, v32, v62
	v_sub_f32_e32 v32, v74, v66
	v_exp_f32_e32 v62, v32
	v_sub_f32_e32 v63, v75, v66
	v_exp_f32_e32 v63, v63
	v_sub_f32_e32 v64, v76, v66
	v_exp_f32_e32 v64, v64
	v_sub_f32_e32 v65, v77, v66
	v_exp_f32_e32 v65, v65
	v_sub_f32_e32 v58, v58, v66
	v_add_f32_e32 v32, 0, v62
	v_exp_f32_e32 v67, v58
	v_sub_f32_e32 v58, v59, v66
	v_add_f32_e32 v32, v63, v32
	v_exp_f32_e32 v68, v58
	v_sub_f32_e32 v58, v60, v66
	v_add_f32_e32 v32, v64, v32
	v_exp_f32_e32 v60, v58
	v_sub_f32_e32 v58, v61, v66
	v_add_f32_e32 v32, v65, v32
	v_exp_f32_e32 v61, v58
	v_sub_f32_e32 v54, v54, v66
	v_add_f32_e32 v32, v67, v32
	v_exp_f32_e32 v54, v54
	v_sub_f32_e32 v55, v55, v66
	v_add_f32_e32 v32, v68, v32
	v_exp_f32_e32 v55, v55
	v_sub_f32_e32 v56, v56, v66
	v_add_f32_e32 v32, v60, v32
	v_exp_f32_e32 v56, v56
	v_sub_f32_e32 v57, v57, v66
	v_add_f32_e32 v32, v61, v32
	v_exp_f32_e32 v57, v57
	v_sub_f32_e32 v50, v50, v66
	v_add_f32_e32 v32, v54, v32
	v_exp_f32_e32 v58, v50
	v_sub_f32_e32 v50, v51, v66
	v_add_f32_e32 v32, v55, v32
	v_exp_f32_e32 v59, v50
	v_sub_f32_e32 v50, v52, v66
	v_add_f32_e32 v32, v56, v32
	v_exp_f32_e32 v52, v50
	v_sub_f32_e32 v50, v53, v66
	v_add_f32_e32 v32, v57, v32
	v_exp_f32_e32 v53, v50
	v_sub_f32_e32 v46, v46, v66
	v_add_f32_e32 v32, v58, v32
	v_exp_f32_e32 v46, v46
	v_sub_f32_e32 v47, v47, v66
	v_add_f32_e32 v32, v59, v32
	v_exp_f32_e32 v47, v47
	v_sub_f32_e32 v48, v48, v66
	v_add_f32_e32 v32, v52, v32
	v_exp_f32_e32 v48, v48
	v_sub_f32_e32 v49, v49, v66
	v_add_f32_e32 v32, v53, v32
	v_exp_f32_e32 v49, v49
	v_sub_f32_e32 v42, v42, v66
	v_add_f32_e32 v32, v46, v32
	v_exp_f32_e32 v50, v42
	v_sub_f32_e32 v42, v43, v66
	v_add_f32_e32 v32, v47, v32
	v_exp_f32_e32 v51, v42
	v_sub_f32_e32 v42, v44, v66
	v_add_f32_e32 v32, v48, v32
	v_exp_f32_e32 v44, v42
	v_sub_f32_e32 v42, v45, v66
	v_add_f32_e32 v32, v49, v32
	v_exp_f32_e32 v45, v42
	v_sub_f32_e32 v38, v38, v66
	v_add_f32_e32 v32, v50, v32
	v_exp_f32_e32 v38, v38
	v_sub_f32_e32 v39, v39, v66
	v_add_f32_e32 v32, v51, v32
	v_exp_f32_e32 v39, v39
	v_sub_f32_e32 v40, v40, v66
	v_add_f32_e32 v32, v44, v32
	v_exp_f32_e32 v40, v40
	v_sub_f32_e32 v41, v41, v66
	v_add_f32_e32 v32, v45, v32
	v_exp_f32_e32 v41, v41
	v_sub_f32_e32 v34, v34, v66
	v_add_f32_e32 v32, v38, v32
	v_exp_f32_e32 v42, v34
	v_sub_f32_e32 v34, v35, v66
	v_add_f32_e32 v32, v39, v32
	v_exp_f32_e32 v43, v34
	v_sub_f32_e32 v34, v36, v66
	v_add_f32_e32 v32, v40, v32
	v_exp_f32_e32 v36, v34
	v_sub_f32_e32 v34, v37, v66
	v_add_f32_e32 v32, v41, v32
	v_exp_f32_e32 v37, v34
	v_sub_f32_e32 v28, v28, v66
	v_add_f32_e32 v32, v42, v32
	v_exp_f32_e32 v28, v28
	v_sub_f32_e32 v29, v29, v66
	v_add_f32_e32 v32, v43, v32
	v_exp_f32_e32 v29, v29
	v_sub_f32_e32 v30, v30, v66
	v_add_f32_e32 v32, v36, v32
	v_exp_f32_e32 v30, v30
	v_sub_f32_e32 v31, v31, v66
	v_add_f32_e32 v32, v37, v32
	v_exp_f32_e32 v31, v31
	v_add_f32_e32 v32, v28, v32
	v_add_f32_e32 v32, v29, v32
	v_add_f32_e32 v32, v30, v32
	v_sub_f32_e32 v24, v24, v66
	v_add_f32_e32 v34, v31, v32
	v_exp_f32_e32 v32, v24
	v_sub_f32_e32 v25, v25, v66
	v_sub_f32_e32 v20, v20, v66
	v_exp_f32_e32 v20, v20
	v_add_f32_e32 v24, v32, v34
	v_exp_f32_e32 v34, v25
	v_sub_f32_e32 v25, v26, v66
	v_exp_f32_e32 v35, v25
	v_sub_f32_e32 v25, v27, v66
	v_exp_f32_e32 v27, v25
	v_sub_f32_e32 v21, v21, v66
	v_add_f32_e32 v24, v34, v24
	v_exp_f32_e32 v21, v21
	v_sub_f32_e32 v22, v22, v66
	v_add_f32_e32 v24, v35, v24
	v_exp_f32_e32 v22, v22
	v_sub_f32_e32 v23, v23, v66
	v_add_f32_e32 v24, v27, v24
	v_exp_f32_e32 v23, v23
	v_add_f32_e32 v24, v20, v24
	v_add_f32_e32 v24, v21, v24
	v_add_f32_e32 v24, v22, v24
	v_sub_f32_e32 v16, v16, v66
	v_add_f32_e32 v25, v23, v24
	v_exp_f32_e32 v24, v16
	v_sub_f32_e32 v17, v17, v66
	v_sub_f32_e32 v12, v12, v66
	v_exp_f32_e32 v12, v12
	v_add_f32_e32 v16, v24, v25
	v_exp_f32_e32 v25, v17
	v_sub_f32_e32 v17, v18, v66
	v_exp_f32_e32 v26, v17
	v_sub_f32_e32 v17, v19, v66
	v_exp_f32_e32 v19, v17
	v_sub_f32_e32 v13, v13, v66
	v_add_f32_e32 v16, v25, v16
	v_exp_f32_e32 v13, v13
	v_sub_f32_e32 v14, v14, v66
	v_add_f32_e32 v16, v26, v16
	v_exp_f32_e32 v14, v14
	v_sub_f32_e32 v15, v15, v66
	v_add_f32_e32 v16, v19, v16
	v_exp_f32_e32 v15, v15
	v_add_f32_e32 v16, v12, v16
	v_add_f32_e32 v16, v13, v16
	v_add_f32_e32 v16, v14, v16
	v_sub_f32_e32 v8, v8, v66
	v_add_f32_e32 v17, v15, v16
	v_exp_f32_e32 v16, v8
	v_sub_f32_e32 v9, v9, v66
	v_sub_f32_e32 v4, v4, v66
	v_exp_f32_e32 v4, v4
	v_add_f32_e32 v8, v16, v17
	v_exp_f32_e32 v17, v9
	v_sub_f32_e32 v9, v10, v66
	v_exp_f32_e32 v18, v9
	v_sub_f32_e32 v9, v11, v66
	v_exp_f32_e32 v11, v9
	v_sub_f32_e32 v5, v5, v66
	v_add_f32_e32 v8, v17, v8
	v_exp_f32_e32 v5, v5
	v_sub_f32_e32 v6, v6, v66
	v_add_f32_e32 v8, v18, v8
	v_exp_f32_e32 v6, v6
	v_sub_f32_e32 v7, v7, v66
	v_add_f32_e32 v8, v11, v8
	v_exp_f32_e32 v7, v7
	v_add_f32_e32 v8, v4, v8
	v_add_f32_e32 v8, v5, v8
	v_add_f32_e32 v8, v6, v8
	v_sub_f32_e32 v0, v0, v66
	v_add_f32_e32 v9, v7, v8
	v_exp_f32_e32 v8, v0
	v_sub_f32_e32 v1, v1, v66
	v_cvt_pk_bf16_f32 v62, v62, v63
	v_cvt_pk_bf16_f32 v63, v64, v65
	v_add_f32_e32 v0, v8, v9
	v_exp_f32_e32 v9, v1
	v_sub_f32_e32 v1, v2, v66
	v_exp_f32_e32 v10, v1
	v_sub_f32_e32 v1, v3, v66
	v_lshlrev_b32_e32 v66, 3, v98
	v_mul_u32_u24_e32 v2, 0x120, v105
	v_and_b32_e32 v66, 24, v66
	v_add3_u32 v2, s27, v2, v66
	v_cvt_pk_bf16_f32 v64, v67, v68
	ds_read_b64_tr_b16 v[68:69], v2 offset:4608
	ds_read_b64_tr_b16 v[66:67], v2
	ds_read_b64_tr_b16 v[70:71], v2 offset:32
	ds_read_b64_tr_b16 v[72:73], v2 offset:4640
	ds_read_b64_tr_b16 v[74:75], v2 offset:64
	ds_read_b64_tr_b16 v[76:77], v2 offset:4672
	ds_read_b64_tr_b16 v[106:107], v2 offset:96
	ds_read_b64_tr_b16 v[108:109], v2 offset:4704
	ds_read_b64_tr_b16 v[110:111], v2 offset:128
	ds_read_b64_tr_b16 v[112:113], v2 offset:4736
	ds_read_b64_tr_b16 v[114:115], v2 offset:160
	ds_read_b64_tr_b16 v[116:117], v2 offset:4768
	ds_read_b64_tr_b16 v[118:119], v2 offset:192
	ds_read_b64_tr_b16 v[120:121], v2 offset:4800
	ds_read_b64_tr_b16 v[122:123], v2 offset:224
	ds_read_b64_tr_b16 v[124:125], v2 offset:4832
	v_exp_f32_e32 v3, v1
	v_add_f32_e32 v0, v9, v0
	v_add_f32_e32 v0, v10, v0
	v_cvt_pk_bf16_f32 v65, v60, v61
	v_add_f32_e32 v0, v3, v0
	ds_bpermute_b32 v1, v100, v0
	s_waitcnt lgkmcnt(0)
	v_add_f32_e32 v0, v0, v1
	ds_bpermute_b32 v1, v101, v0
	v_mfma_f32_16x16x32_bf16 v[66:69], v[66:69], v[62:65], 0
	v_mfma_f32_16x16x32_bf16 v[70:73], v[70:73], v[62:65], 0
	v_mfma_f32_16x16x32_bf16 v[74:77], v[74:77], v[62:65], 0
	v_mfma_f32_16x16x32_bf16 v[106:109], v[106:109], v[62:65], 0
	v_mfma_f32_16x16x32_bf16 v[110:113], v[110:113], v[62:65], 0
	v_mfma_f32_16x16x32_bf16 v[114:117], v[114:117], v[62:65], 0
	v_mfma_f32_16x16x32_bf16 v[118:121], v[118:121], v[62:65], 0
	v_mfma_f32_16x16x32_bf16 v[60:63], v[122:125], v[62:65], 0
	ds_read_b64_tr_b16 v[124:125], v2 offset:13824
	ds_read_b64_tr_b16 v[122:123], v2 offset:9216
	ds_read_b64_tr_b16 v[126:127], v2 offset:9248
	ds_read_b64_tr_b16 v[128:129], v2 offset:13856
	ds_read_b64_tr_b16 v[130:131], v2 offset:9280
	ds_read_b64_tr_b16 v[132:133], v2 offset:13888
	ds_read_b64_tr_b16 v[134:135], v2 offset:9312
	ds_read_b64_tr_b16 v[136:137], v2 offset:13920
	ds_read_b64_tr_b16 v[138:139], v2 offset:9344
	ds_read_b64_tr_b16 v[140:141], v2 offset:13952
	ds_read_b64_tr_b16 v[142:143], v2 offset:9376
	ds_read_b64_tr_b16 v[144:145], v2 offset:13984
	ds_read_b64_tr_b16 v[146:147], v2 offset:9408
	ds_read_b64_tr_b16 v[148:149], v2 offset:14016
	ds_read_b64_tr_b16 v[150:151], v2 offset:9440
	ds_read_b64_tr_b16 v[152:153], v2 offset:14048
	v_cvt_pk_bf16_f32 v54, v54, v55
	v_cvt_pk_bf16_f32 v55, v56, v57
	v_cvt_pk_bf16_f32 v56, v58, v59
	v_cvt_pk_bf16_f32 v57, v52, v53
	s_waitcnt lgkmcnt(14)
	v_mfma_f32_16x16x32_bf16 v[64:67], v[122:125], v[54:57], v[66:69]
	s_waitcnt lgkmcnt(12)
	v_mfma_f32_16x16x32_bf16 v[68:71], v[126:129], v[54:57], v[70:73]
	s_waitcnt lgkmcnt(10)
	v_mfma_f32_16x16x32_bf16 v[72:75], v[130:133], v[54:57], v[74:77]
	s_waitcnt lgkmcnt(8)
	v_mfma_f32_16x16x32_bf16 v[106:109], v[134:137], v[54:57], v[106:109]
	s_waitcnt lgkmcnt(6)
	v_mfma_f32_16x16x32_bf16 v[110:113], v[138:141], v[54:57], v[110:113]
	s_waitcnt lgkmcnt(4)
	v_mfma_f32_16x16x32_bf16 v[114:117], v[142:145], v[54:57], v[114:117]
	s_waitcnt lgkmcnt(2)
	v_mfma_f32_16x16x32_bf16 v[118:121], v[146:149], v[54:57], v[118:121]
	s_waitcnt lgkmcnt(0)
	v_mfma_f32_16x16x32_bf16 v[52:55], v[150:153], v[54:57], v[60:63]
	ds_read_b64_tr_b16 v[58:59], v2 offset:23040
	ds_read_b64_tr_b16 v[56:57], v2 offset:18432
	s_nop 0
	ds_read_b64_tr_b16 v[60:61], v2 offset:18464
	ds_read_b64_tr_b16 v[62:63], v2 offset:23072
	ds_read_b64_tr_b16 v[122:123], v2 offset:18496
	ds_read_b64_tr_b16 v[124:125], v2 offset:23104
	ds_read_b64_tr_b16 v[126:127], v2 offset:18528
	ds_read_b64_tr_b16 v[128:129], v2 offset:23136
	ds_read_b64_tr_b16 v[130:131], v2 offset:18560
	ds_read_b64_tr_b16 v[132:133], v2 offset:23168
	ds_read_b64_tr_b16 v[134:135], v2 offset:18592
	ds_read_b64_tr_b16 v[136:137], v2 offset:23200
	ds_read_b64_tr_b16 v[138:139], v2 offset:18624
	ds_read_b64_tr_b16 v[140:141], v2 offset:23232
	ds_read_b64_tr_b16 v[142:143], v2 offset:18656
	ds_read_b64_tr_b16 v[144:145], v2 offset:23264
	v_cvt_pk_bf16_f32 v46, v46, v47
	v_cvt_pk_bf16_f32 v47, v48, v49
	v_cvt_pk_bf16_f32 v48, v50, v51
	v_cvt_pk_bf16_f32 v49, v44, v45
	s_waitcnt lgkmcnt(14)
	v_mfma_f32_16x16x32_bf16 v[56:59], v[56:59], v[46:49], v[64:67]
	s_waitcnt lgkmcnt(12)
	v_mfma_f32_16x16x32_bf16 v[60:63], v[60:63], v[46:49], v[68:71]
	s_waitcnt lgkmcnt(10)
	v_mfma_f32_16x16x32_bf16 v[64:67], v[122:125], v[46:49], v[72:75]
	s_waitcnt lgkmcnt(8)
	v_mfma_f32_16x16x32_bf16 v[68:71], v[126:129], v[46:49], v[106:109]
	s_waitcnt lgkmcnt(6)
	v_mfma_f32_16x16x32_bf16 v[72:75], v[130:133], v[46:49], v[110:113]
	s_waitcnt lgkmcnt(4)
	v_mfma_f32_16x16x32_bf16 v[106:109], v[134:137], v[46:49], v[114:117]
	s_waitcnt lgkmcnt(2)
	v_mfma_f32_16x16x32_bf16 v[110:113], v[138:141], v[46:49], v[118:121]
	s_waitcnt lgkmcnt(0)
	v_mfma_f32_16x16x32_bf16 v[44:47], v[142:145], v[46:49], v[52:55]
	ds_read_b64_tr_b16 v[50:51], v2 offset:32256
	ds_read_b64_tr_b16 v[48:49], v2 offset:27648
	s_nop 0
	ds_read_b64_tr_b16 v[52:53], v2 offset:27680
	ds_read_b64_tr_b16 v[54:55], v2 offset:32288
	ds_read_b64_tr_b16 v[114:115], v2 offset:27712
	ds_read_b64_tr_b16 v[116:117], v2 offset:32320
	ds_read_b64_tr_b16 v[118:119], v2 offset:27744
	ds_read_b64_tr_b16 v[120:121], v2 offset:32352
	ds_read_b64_tr_b16 v[122:123], v2 offset:27776
	ds_read_b64_tr_b16 v[124:125], v2 offset:32384
	ds_read_b64_tr_b16 v[126:127], v2 offset:27808
	ds_read_b64_tr_b16 v[128:129], v2 offset:32416
	ds_read_b64_tr_b16 v[130:131], v2 offset:27840
	ds_read_b64_tr_b16 v[132:133], v2 offset:32448
	ds_read_b64_tr_b16 v[134:135], v2 offset:27872
	ds_read_b64_tr_b16 v[136:137], v2 offset:32480
	v_cvt_pk_bf16_f32 v38, v38, v39
	v_cvt_pk_bf16_f32 v39, v40, v41
	v_cvt_pk_bf16_f32 v40, v42, v43
	v_cvt_pk_bf16_f32 v41, v36, v37
	s_waitcnt lgkmcnt(14)
	v_mfma_f32_16x16x32_bf16 v[48:51], v[48:51], v[38:41], v[56:59]
	s_waitcnt lgkmcnt(12)
	v_mfma_f32_16x16x32_bf16 v[52:55], v[52:55], v[38:41], v[60:63]
	s_waitcnt lgkmcnt(10)
	v_mfma_f32_16x16x32_bf16 v[56:59], v[114:117], v[38:41], v[64:67]
	s_waitcnt lgkmcnt(8)
	v_mfma_f32_16x16x32_bf16 v[60:63], v[118:121], v[38:41], v[68:71]
	s_waitcnt lgkmcnt(6)
	v_mfma_f32_16x16x32_bf16 v[64:67], v[122:125], v[38:41], v[72:75]
	s_waitcnt lgkmcnt(4)
	v_mfma_f32_16x16x32_bf16 v[68:71], v[126:129], v[38:41], v[106:109]
	s_waitcnt lgkmcnt(2)
	v_mfma_f32_16x16x32_bf16 v[72:75], v[130:133], v[38:41], v[110:113]
	s_waitcnt lgkmcnt(0)
	v_mfma_f32_16x16x32_bf16 v[36:39], v[134:137], v[38:41], v[44:47]
	ds_read_b64_tr_b16 v[42:43], v2 offset:41472
	ds_read_b64_tr_b16 v[40:41], v2 offset:36864
	s_nop 0
	ds_read_b64_tr_b16 v[44:45], v2 offset:36896
	ds_read_b64_tr_b16 v[46:47], v2 offset:41504
	ds_read_b64_tr_b16 v[106:107], v2 offset:36928
	ds_read_b64_tr_b16 v[108:109], v2 offset:41536
	ds_read_b64_tr_b16 v[110:111], v2 offset:36960
	ds_read_b64_tr_b16 v[112:113], v2 offset:41568
	ds_read_b64_tr_b16 v[114:115], v2 offset:36992
	ds_read_b64_tr_b16 v[116:117], v2 offset:41600
	ds_read_b64_tr_b16 v[118:119], v2 offset:37024
	ds_read_b64_tr_b16 v[120:121], v2 offset:41632
	ds_read_b64_tr_b16 v[122:123], v2 offset:37056
	ds_read_b64_tr_b16 v[124:125], v2 offset:41664
	ds_read_b64_tr_b16 v[126:127], v2 offset:37088
	ds_read_b64_tr_b16 v[128:129], v2 offset:41696
	v_cvt_pk_bf16_f32 v28, v28, v29
	v_cvt_pk_bf16_f32 v29, v30, v31
	v_cvt_pk_bf16_f32 v30, v32, v34
	v_cvt_pk_bf16_f32 v31, v35, v27
	s_waitcnt lgkmcnt(14)
	v_mfma_f32_16x16x32_bf16 v[40:43], v[40:43], v[28:31], v[48:51]
	s_waitcnt lgkmcnt(12)
	v_mfma_f32_16x16x32_bf16 v[44:47], v[44:47], v[28:31], v[52:55]
	s_waitcnt lgkmcnt(10)
	v_mfma_f32_16x16x32_bf16 v[48:51], v[106:109], v[28:31], v[56:59]
	s_waitcnt lgkmcnt(8)
	v_mfma_f32_16x16x32_bf16 v[52:55], v[110:113], v[28:31], v[60:63]
	s_waitcnt lgkmcnt(6)
	v_mfma_f32_16x16x32_bf16 v[56:59], v[114:117], v[28:31], v[64:67]
	s_waitcnt lgkmcnt(4)
	v_mfma_f32_16x16x32_bf16 v[60:63], v[118:121], v[28:31], v[68:71]
	s_waitcnt lgkmcnt(2)
	v_mfma_f32_16x16x32_bf16 v[64:67], v[122:125], v[28:31], v[72:75]
	s_waitcnt lgkmcnt(0)
	v_mfma_f32_16x16x32_bf16 v[28:31], v[126:129], v[28:31], v[36:39]
	v_cvt_pk_bf16_f32 v20, v20, v21
	v_cvt_pk_bf16_f32 v21, v22, v23
	v_cvt_pk_bf16_f32 v22, v24, v25
	v_cvt_pk_bf16_f32 v23, v26, v19
	ds_read_b64_tr_b16 v[26:27], v2 offset:50688
	ds_read_b64_tr_b16 v[24:25], v2 offset:46080
	ds_read_b64_tr_b16 v[34:35], v2 offset:46112
	ds_read_b64_tr_b16 v[36:37], v2 offset:50720
	ds_read_b64_tr_b16 v[68:69], v2 offset:46144
	ds_read_b64_tr_b16 v[70:71], v2 offset:50752
	ds_read_b64_tr_b16 v[72:73], v2 offset:46176
	ds_read_b64_tr_b16 v[74:75], v2 offset:50784
	ds_read_b64_tr_b16 v[106:107], v2 offset:46208
	ds_read_b64_tr_b16 v[108:109], v2 offset:50816
	ds_read_b64_tr_b16 v[110:111], v2 offset:46240
	ds_read_b64_tr_b16 v[112:113], v2 offset:50848
	ds_read_b64_tr_b16 v[114:115], v2 offset:46272
	ds_read_b64_tr_b16 v[116:117], v2 offset:50880
	ds_read_b64_tr_b16 v[118:119], v2 offset:46304
	ds_read_b64_tr_b16 v[120:121], v2 offset:50912
	s_waitcnt lgkmcnt(14)
	v_mfma_f32_16x16x32_bf16 v[24:27], v[24:27], v[20:23], v[40:43]
	s_waitcnt lgkmcnt(12)
	v_mfma_f32_16x16x32_bf16 v[34:37], v[34:37], v[20:23], v[44:47]
	s_waitcnt lgkmcnt(10)
	v_mfma_f32_16x16x32_bf16 v[38:41], v[68:71], v[20:23], v[48:51]
	s_waitcnt lgkmcnt(8)
	v_mfma_f32_16x16x32_bf16 v[42:45], v[72:75], v[20:23], v[52:55]
	s_waitcnt lgkmcnt(6)
	v_mfma_f32_16x16x32_bf16 v[46:49], v[106:109], v[20:23], v[56:59]
	s_waitcnt lgkmcnt(4)
	v_mfma_f32_16x16x32_bf16 v[50:53], v[110:113], v[20:23], v[60:63]
	s_waitcnt lgkmcnt(2)
	v_mfma_f32_16x16x32_bf16 v[54:57], v[114:117], v[20:23], v[64:67]
	s_waitcnt lgkmcnt(0)
	v_mfma_f32_16x16x32_bf16 v[20:23], v[118:121], v[20:23], v[28:31]
	v_cvt_pk_bf16_f32 v12, v12, v13
	v_cvt_pk_bf16_f32 v13, v14, v15
	v_cvt_pk_bf16_f32 v14, v16, v17
	v_cvt_pk_bf16_f32 v15, v18, v11
	ds_read_b64_tr_b16 v[18:19], v2 offset:59904
	ds_read_b64_tr_b16 v[16:17], v2 offset:55296
	s_nop 0
	ds_read_b64_tr_b16 v[28:29], v2 offset:55328
	ds_read_b64_tr_b16 v[30:31], v2 offset:59936
	ds_read_b64_tr_b16 v[58:59], v2 offset:55360
	ds_read_b64_tr_b16 v[60:61], v2 offset:59968
	ds_read_b64_tr_b16 v[62:63], v2 offset:55392
	ds_read_b64_tr_b16 v[64:65], v2 offset:60000
	ds_read_b64_tr_b16 v[66:67], v2 offset:55424
	ds_read_b64_tr_b16 v[68:69], v2 offset:60032
	ds_read_b64_tr_b16 v[70:71], v2 offset:55456
	ds_read_b64_tr_b16 v[72:73], v2 offset:60064
	ds_read_b64_tr_b16 v[74:75], v2 offset:55488
	ds_read_b64_tr_b16 v[76:77], v2 offset:60096
	ds_read_b64_tr_b16 v[106:107], v2 offset:55520
	ds_read_b64_tr_b16 v[108:109], v2 offset:60128
	s_waitcnt lgkmcnt(14)
	v_mfma_f32_16x16x32_bf16 v[16:19], v[16:19], v[12:15], v[24:27]
	s_waitcnt lgkmcnt(12)
	v_mfma_f32_16x16x32_bf16 v[24:27], v[28:31], v[12:15], v[34:37]
	s_waitcnt lgkmcnt(10)
	v_mfma_f32_16x16x32_bf16 v[28:31], v[58:61], v[12:15], v[38:41]
	s_waitcnt lgkmcnt(8)
	v_mfma_f32_16x16x32_bf16 v[34:37], v[62:65], v[12:15], v[42:45]
	s_waitcnt lgkmcnt(6)
	v_mfma_f32_16x16x32_bf16 v[38:41], v[66:69], v[12:15], v[46:49]
	s_waitcnt lgkmcnt(4)
	v_mfma_f32_16x16x32_bf16 v[42:45], v[70:73], v[12:15], v[50:53]
	s_waitcnt lgkmcnt(2)
	v_mfma_f32_16x16x32_bf16 v[46:49], v[74:77], v[12:15], v[54:57]
	s_waitcnt lgkmcnt(0)
	v_mfma_f32_16x16x32_bf16 v[12:15], v[106:109], v[12:15], v[20:23]
	v_cvt_pk_bf16_f32 v4, v4, v5
	v_cvt_pk_bf16_f32 v5, v6, v7
	v_cvt_pk_bf16_f32 v7, v10, v3
	v_add_u32_e32 v3, 0x10e00, v2
	v_cvt_pk_bf16_f32 v6, v8, v9
	ds_read_b64_tr_b16 v[10:11], v3
	ds_read_b64_tr_b16 v[8:9], v2 offset:64512
	ds_read_b64_tr_b16 v[20:21], v2 offset:64544
	v_add_u32_e32 v3, 0x10e20, v2
	ds_read_b64_tr_b16 v[22:23], v3
	ds_read_b64_tr_b16 v[50:51], v2 offset:64576
	v_add_u32_e32 v3, 0x10e40, v2
	ds_read_b64_tr_b16 v[52:53], v3
	ds_read_b64_tr_b16 v[54:55], v2 offset:64608
	v_add_u32_e32 v3, 0x10e60, v2
	ds_read_b64_tr_b16 v[56:57], v3
	ds_read_b64_tr_b16 v[58:59], v2 offset:64640
	v_add_u32_e32 v3, 0x10e80, v2
	ds_read_b64_tr_b16 v[60:61], v3
	ds_read_b64_tr_b16 v[62:63], v2 offset:64672
	v_add_u32_e32 v3, 0x10ea0, v2
	ds_read_b64_tr_b16 v[64:65], v3
	ds_read_b64_tr_b16 v[66:67], v2 offset:64704
	v_add_u32_e32 v3, 0x10ec0, v2
	ds_read_b64_tr_b16 v[68:69], v3
	ds_read_b64_tr_b16 v[70:71], v2 offset:64736
	v_add_u32_e32 v2, 0x10ee0, v2
	ds_read_b64_tr_b16 v[72:73], v2
	s_waitcnt lgkmcnt(14)
	v_mfma_f32_16x16x32_bf16 v[8:11], v[8:11], v[4:7], v[16:19]
	s_waitcnt lgkmcnt(12)
	v_mfma_f32_16x16x32_bf16 v[16:19], v[20:23], v[4:7], v[24:27]
	s_waitcnt lgkmcnt(10)
	v_mfma_f32_16x16x32_bf16 v[20:23], v[50:53], v[4:7], v[28:31]
	s_waitcnt lgkmcnt(8)
	v_mfma_f32_16x16x32_bf16 v[24:27], v[54:57], v[4:7], v[34:37]
	s_waitcnt lgkmcnt(6)
	v_mfma_f32_16x16x32_bf16 v[28:31], v[58:61], v[4:7], v[38:41]
	s_waitcnt lgkmcnt(4)
	v_mfma_f32_16x16x32_bf16 v[34:37], v[62:65], v[4:7], v[42:45]
	s_waitcnt lgkmcnt(2)
	v_mfma_f32_16x16x32_bf16 v[38:41], v[66:69], v[4:7], v[46:49]
	s_waitcnt lgkmcnt(0)
	v_mfma_f32_16x16x32_bf16 v[2:5], v[70:73], v[4:7], v[12:15]
	v_add_f32_e32 v0, v0, v1
	v_rcp_f32_e32 v6, v0
	s_waitcnt vmcnt(7)
	v_lshlrev_b32_e32 v0, 16, v96
	v_and_b32_e32 v1, 0xffff0000, v96
	s_mov_b64 s[10:11], 0
	v_mul_f32_e32 v7, v6, v8
	v_mul_f32_e32 v8, v6, v9
	v_mul_f32_e32 v0, v7, v0
	v_mul_f32_e32 v1, v8, v1
	v_cvt_pk_bf16_f32 v0, v0, v1
	v_mul_f32_e32 v1, v6, v10
	v_lshlrev_b32_e32 v7, 16, v97
	v_mul_f32_e32 v1, v1, v7
	v_mul_f32_e32 v7, v6, v11
	v_and_b32_e32 v8, 0xffff0000, v97
	v_mul_f32_e32 v7, v7, v8
	v_cvt_pk_bf16_f32 v1, v1, v7
	global_store_dwordx2 v[94:95], v[0:1], off
	v_mul_f32_e32 v0, v6, v16
	s_waitcnt vmcnt(7)
	v_lshlrev_b32_e32 v1, 16, v92
	v_mul_f32_e32 v0, v0, v1
	v_mul_f32_e32 v1, v6, v17
	v_and_b32_e32 v7, 0xffff0000, v92
	v_mul_f32_e32 v1, v1, v7
	v_cvt_pk_bf16_f32 v0, v0, v1
	v_mul_f32_e32 v1, v6, v18
	v_lshlrev_b32_e32 v7, 16, v93
	v_mul_f32_e32 v1, v1, v7
	v_mul_f32_e32 v7, v6, v19
	v_and_b32_e32 v8, 0xffff0000, v93
	v_mul_f32_e32 v7, v7, v8
	v_cvt_pk_bf16_f32 v1, v1, v7
	global_store_dwordx2 v[78:79], v[0:1], off offset:32
	v_mul_f32_e32 v0, v6, v20
	s_waitcnt vmcnt(7)
	v_lshlrev_b32_e32 v1, 16, v90
	v_mul_f32_e32 v0, v0, v1
	v_mul_f32_e32 v1, v6, v21
	v_and_b32_e32 v7, 0xffff0000, v90
	v_mul_f32_e32 v1, v1, v7
	v_cvt_pk_bf16_f32 v0, v0, v1
	v_mul_f32_e32 v1, v6, v22
	v_lshlrev_b32_e32 v7, 16, v91
	v_mul_f32_e32 v1, v1, v7
	v_mul_f32_e32 v7, v6, v23
	v_and_b32_e32 v8, 0xffff0000, v91
	v_mul_f32_e32 v7, v7, v8
	v_cvt_pk_bf16_f32 v1, v1, v7
	global_store_dwordx2 v[78:79], v[0:1], off offset:64
	v_mul_f32_e32 v0, v6, v24
	s_waitcnt vmcnt(7)
	v_lshlrev_b32_e32 v1, 16, v88
	v_mul_f32_e32 v0, v0, v1
	v_mul_f32_e32 v1, v6, v25
	v_and_b32_e32 v7, 0xffff0000, v88
	v_mul_f32_e32 v1, v1, v7
	v_cvt_pk_bf16_f32 v0, v0, v1
	v_mul_f32_e32 v1, v6, v26
	v_lshlrev_b32_e32 v7, 16, v89
	v_mul_f32_e32 v1, v1, v7
	v_mul_f32_e32 v7, v6, v27
	v_and_b32_e32 v8, 0xffff0000, v89
	v_mul_f32_e32 v7, v7, v8
	v_cvt_pk_bf16_f32 v1, v1, v7
	global_store_dwordx2 v[78:79], v[0:1], off offset:96
	v_mul_f32_e32 v0, v6, v28
	s_waitcnt vmcnt(7)
	v_lshlrev_b32_e32 v1, 16, v86
	v_mul_f32_e32 v0, v0, v1
	v_mul_f32_e32 v1, v6, v29
	v_and_b32_e32 v7, 0xffff0000, v86
	v_mul_f32_e32 v1, v1, v7
	v_cvt_pk_bf16_f32 v0, v0, v1
	v_mul_f32_e32 v1, v6, v30
	v_lshlrev_b32_e32 v7, 16, v87
	v_mul_f32_e32 v1, v1, v7
	v_mul_f32_e32 v7, v6, v31
	v_and_b32_e32 v8, 0xffff0000, v87
	v_mul_f32_e32 v7, v7, v8
	v_cvt_pk_bf16_f32 v1, v1, v7
	global_store_dwordx2 v[78:79], v[0:1], off offset:128
	v_mul_f32_e32 v0, v6, v34
	s_waitcnt vmcnt(7)
	v_lshlrev_b32_e32 v1, 16, v84
	v_mul_f32_e32 v0, v0, v1
	v_mul_f32_e32 v1, v6, v35
	v_and_b32_e32 v7, 0xffff0000, v84
	v_mul_f32_e32 v1, v1, v7
	v_cvt_pk_bf16_f32 v0, v0, v1
	v_mul_f32_e32 v1, v6, v36
	v_lshlrev_b32_e32 v7, 16, v85
	v_mul_f32_e32 v1, v1, v7
	v_mul_f32_e32 v7, v6, v37
	v_and_b32_e32 v8, 0xffff0000, v85
	v_mul_f32_e32 v7, v7, v8
	v_cvt_pk_bf16_f32 v1, v1, v7
	global_store_dwordx2 v[78:79], v[0:1], off offset:160
	v_mul_f32_e32 v0, v6, v38
	s_waitcnt vmcnt(7)
	v_lshlrev_b32_e32 v1, 16, v82
	v_mul_f32_e32 v0, v0, v1
	v_mul_f32_e32 v1, v6, v39
	v_and_b32_e32 v7, 0xffff0000, v82
	v_mul_f32_e32 v1, v1, v7
	v_cvt_pk_bf16_f32 v0, v0, v1
	v_mul_f32_e32 v1, v6, v40
	v_lshlrev_b32_e32 v7, 16, v83
	v_mul_f32_e32 v1, v1, v7
	v_mul_f32_e32 v7, v6, v41
	v_and_b32_e32 v8, 0xffff0000, v83
	v_mul_f32_e32 v7, v7, v8
	v_cvt_pk_bf16_f32 v1, v1, v7
	global_store_dwordx2 v[78:79], v[0:1], off offset:192
	v_mul_f32_e32 v0, v6, v2
	s_waitcnt vmcnt(7)
	v_lshlrev_b32_e32 v1, 16, v80
	v_mul_f32_e32 v0, v0, v1
	v_mul_f32_e32 v1, v6, v3
	v_and_b32_e32 v2, 0xffff0000, v80
	v_mul_f32_e32 v1, v1, v2
	v_cvt_pk_bf16_f32 v0, v0, v1
	v_mul_f32_e32 v1, v6, v4
	v_lshlrev_b32_e32 v2, 16, v81
	v_mul_f32_e32 v1, v1, v2
	v_mul_f32_e32 v2, v6, v5
	v_and_b32_e32 v3, 0xffff0000, v81
	v_mul_f32_e32 v2, v2, v3
	v_cvt_pk_bf16_f32 v1, v1, v2
	global_store_dwordx2 v[78:79], v[0:1], off offset:224
	s_barrier
